# RES_MIX/RES_FFN: co-resident blocks staggered by ~8us at the first tile (spread epilogue memory bursts)
# speedup vs baseline: 1.0019x; 1.0019x over previous
.LBB0_703:
	s_ashr_i32 s6, s3, 31
	s_lshr_b32 s6, s6, 26
	s_add_i32 s6, s3, s6
	s_ashr_i32 s58, s6, 6
	s_andn2_b32 s6, s6, 63
	s_sub_i32 s6, s3, s6
	s_ashr_i32 s59, s6, 31
	s_lshr_b32 s59, s59, 29
	s_add_i32 s59, s6, s59
	s_ashr_i32 s69, s59, 3
	s_and_b32 s59, s59, -8
	s_lshl_b32 s58, s58, 3
	s_sub_i32 s6, s6, s59
	s_add_i32 s6, s6, s58
	s_lshl_b32 s64, s6, 7
	s_ashr_i32 s65, s64, 31
	s_lshl_b32 s66, s69, 7
	s_lshl_b64 s[58:59], s[64:65], 11
	s_ashr_i32 s67, s66, 31
	s_cmp_eq_u32 s39, 1
	s_cbranch_scc1 .Lgk_pfhead_p6
	s_bitcmp0_b32 s2, 8
	s_cbranch_scc1 .Lgk_nostag_p6
	s_sleep 127
	s_sleep 127
.Lgk_nostag_p6:
	s_lshl_b32 s38, s64, 11
	s_add_u32 s18, s14, s38
	s_addc_u32 s19, s15, 0
	s_add_u32 s18, s18, 0xb79f000
	s_addc_u32 s19, s19, 0
	s_add_u32 s20, s18, 0x10000
	s_addc_u32 s21, s19, 0
	s_add_u32 s22, s20, 0x10000
	s_addc_u32 s23, s21, 0
	s_add_u32 s24, s22, 0x10000
	s_addc_u32 s25, s23, 0
	s_lshl_b32 s38, s66, 11
	s_add_u32 s26, s14, s38
	s_addc_u32 s27, s15, 0
	s_add_u32 s26, s26, 0x3a0000
	s_addc_u32 s27, s27, 0
	s_add_u32 s28, s26, 0x10000
	s_addc_u32 s29, s27, 0
	s_add_u32 s30, s28, 0x10000
	s_addc_u32 s31, s29, 0
	s_add_u32 s34, s30, 0x10000
	s_addc_u32 s35, s31, 0
	v_readfirstlane_b32 s36, v142
	v_mov_b32_e32 v254, v64
	s_mov_b32 m0, s36
	s_nop 0
	global_load_lds_dwordx4 v254, s[18:19]
	s_add_u32 m0, m0, 0x1000
	s_nop 0
	global_load_lds_dwordx4 v254, s[20:21]
	s_add_u32 m0, m0, 0x1000
	s_nop 0
	global_load_lds_dwordx4 v254, s[22:23]
	s_add_u32 m0, m0, 0x1000
	s_nop 0
	global_load_lds_dwordx4 v254, s[24:25]
	s_add_u32 m0, m0, 0x1000
	s_nop 0
	global_load_lds_dwordx4 v254, s[26:27]
	s_add_u32 m0, m0, 0x1000
	s_nop 0
	global_load_lds_dwordx4 v254, s[28:29]
	s_add_u32 m0, m0, 0x1000
	s_nop 0
	global_load_lds_dwordx4 v254, s[30:31]
	s_add_u32 m0, m0, 0x1000
	s_nop 0
	global_load_lds_dwordx4 v254, s[34:35]
	v_add_u32_e32 v254, 0x80, v254
	s_add_u32 m0, s36, 0x8000
	s_nop 0
	global_load_lds_dwordx4 v254, s[18:19]
	s_add_u32 m0, m0, 0x1000
	s_nop 0
	global_load_lds_dwordx4 v254, s[20:21]
	s_add_u32 m0, m0, 0x1000
	s_nop 0
	global_load_lds_dwordx4 v254, s[22:23]
	s_add_u32 m0, m0, 0x1000
	s_nop 0
	global_load_lds_dwordx4 v254, s[24:25]
	s_add_u32 m0, m0, 0x1000
	s_nop 0
	global_load_lds_dwordx4 v254, s[26:27]
	s_add_u32 m0, m0, 0x1000
	s_nop 0
	global_load_lds_dwordx4 v254, s[28:29]
	s_add_u32 m0, m0, 0x1000
	s_nop 0
	global_load_lds_dwordx4 v254, s[30:31]
	s_add_u32 m0, m0, 0x1000
	s_nop 0
	global_load_lds_dwordx4 v254, s[34:35]
	v_add_u32_e32 v254, 0x80, v254

.LBB0_775:
	s_ashr_i32 s6, s3, 31
	s_lshr_b32 s6, s6, 26
	s_add_i32 s6, s3, s6
	s_ashr_i32 s58, s6, 6
	s_andn2_b32 s6, s6, 63
	s_sub_i32 s6, s3, s6
	s_ashr_i32 s59, s6, 31
	s_lshr_b32 s59, s59, 29
	s_add_i32 s59, s6, s59
	s_ashr_i32 s64, s59, 3
	s_and_b32 s59, s59, -8
	s_lshl_b32 s58, s58, 3
	s_sub_i32 s6, s6, s59
	s_add_i32 s6, s6, s58
	s_lshl_b32 s67, s6, 7
	s_lshl_b32 s68, s64, 7
	s_waitcnt lgkmcnt(0)
	s_cmp_eq_u32 s39, 1
	s_cbranch_scc1 .Lgk_pfhead_p8
	s_bitcmp0_b32 s2, 8
	s_cbranch_scc1 .Lgk_nostag_p8
	s_sleep 127
	s_sleep 127
.Lgk_nostag_p8:
	s_mul_i32 s38, s6, 0xb0000
	s_add_u32 s18, s14, s38
	s_addc_u32 s19, s15, 0
	s_add_u32 s18, s18, 0x879f000
	s_addc_u32 s19, s19, 0
	s_add_u32 s20, s18, 0x2c000
	s_addc_u32 s21, s19, 0
	s_add_u32 s22, s20, 0x2c000
	s_addc_u32 s23, s21, 0
	s_add_u32 s24, s22, 0x2c000
	s_addc_u32 s25, s23, 0
	s_mul_i32 s38, s64, 0xb0000
	s_add_u32 s26, s14, s38
	s_addc_u32 s27, s15, 0
	s_add_u32 s26, s26, 0x45a0000
	s_addc_u32 s27, s27, 0
	s_add_u32 s28, s26, 0x2c000
	s_addc_u32 s29, s27, 0
	s_add_u32 s30, s28, 0x2c000
	s_addc_u32 s31, s29, 0
	s_add_u32 s34, s30, 0x2c000
	s_addc_u32 s35, s31, 0
	v_readfirstlane_b32 s36, v141
	v_mov_b32_e32 v254, v64
	s_mov_b32 m0, s36
	s_nop 0
	global_load_lds_dwordx4 v254, s[18:19]
	s_add_u32 m0, m0, 0x1000
	s_nop 0
	global_load_lds_dwordx4 v254, s[20:21]
	s_add_u32 m0, m0, 0x1000
	s_nop 0
	global_load_lds_dwordx4 v254, s[22:23]
	s_add_u32 m0, m0, 0x1000
	s_nop 0
	global_load_lds_dwordx4 v254, s[24:25]
	s_add_u32 m0, m0, 0x1000
	s_nop 0
	global_load_lds_dwordx4 v254, s[26:27]
	s_add_u32 m0, m0, 0x1000
	s_nop 0
	global_load_lds_dwordx4 v254, s[28:29]
	s_add_u32 m0, m0, 0x1000
	s_nop 0
	global_load_lds_dwordx4 v254, s[30:31]
	s_add_u32 m0, m0, 0x1000
	s_nop 0
	global_load_lds_dwordx4 v254, s[34:35]
	v_add_u32_e32 v254, 0x80, v254
	s_add_u32 m0, s36, 0x8000
	s_nop 0
	global_load_lds_dwordx4 v254, s[18:19]
	s_add_u32 m0, m0, 0x1000
	s_nop 0
	global_load_lds_dwordx4 v254, s[20:21]
	s_add_u32 m0, m0, 0x1000
	s_nop 0
	global_load_lds_dwordx4 v254, s[22:23]
	s_add_u32 m0, m0, 0x1000
	s_nop 0
	global_load_lds_dwordx4 v254, s[24:25]
	s_add_u32 m0, m0, 0x1000
	s_nop 0
	global_load_lds_dwordx4 v254, s[26:27]
	s_add_u32 m0, m0, 0x1000
	s_nop 0
	global_load_lds_dwordx4 v254, s[28:29]
	s_add_u32 m0, m0, 0x1000
	s_nop 0
	global_load_lds_dwordx4 v254, s[30:31]
	s_add_u32 m0, m0, 0x1000
	s_nop 0
	global_load_lds_dwordx4 v254, s[34:35]
	v_add_u32_e32 v254, 0x80, v254

.LBB0_1046:
	s_ashr_i32 s6, s3, 31
	s_lshr_b32 s6, s6, 26
	s_add_i32 s6, s3, s6
	s_ashr_i32 s58, s6, 6
	s_andn2_b32 s6, s6, 63
	s_sub_i32 s6, s3, s6
	s_ashr_i32 s59, s6, 31
	s_lshr_b32 s59, s59, 29
	s_add_i32 s59, s6, s59
	s_ashr_i32 s64, s59, 3
	s_and_b32 s59, s59, -8
	s_lshl_b32 s58, s58, 3
	s_sub_i32 s6, s6, s59
	s_add_i32 s6, s6, s58
	s_lshl_b32 s66, s6, 7
	s_ashr_i32 s67, s66, 31
	s_lshl_b32 s68, s64, 7
	s_lshl_b64 s[58:59], s[66:67], 11
	s_ashr_i32 s69, s68, 31
	s_cmp_eq_u32 s39, 1
	s_cbranch_scc1 .Lgk_pfhead_p11
	s_bitcmp0_b32 s2, 8
	s_cbranch_scc1 .Lgk_nostag_p11
	s_sleep 127
	s_sleep 127
.Lgk_nostag_p11:
	s_lshl_b32 s38, s66, 11
	s_add_u32 s18, s14, s38
	s_addc_u32 s19, s15, 0
	s_add_u32 s18, s18, 0xb79f000
	s_addc_u32 s19, s19, 0
	s_add_u32 s20, s18, 0x10000
	s_addc_u32 s21, s19, 0
	s_add_u32 s22, s20, 0x10000
	s_addc_u32 s23, s21, 0
	s_add_u32 s24, s22, 0x10000
	s_addc_u32 s25, s23, 0
	s_lshl_b32 s38, s68, 11
	s_add_u32 s26, s14, s38
	s_addc_u32 s27, s15, 0
	s_add_u32 s26, s26, 0xba0000
	s_addc_u32 s27, s27, 0
	s_add_u32 s28, s26, 0x10000
	s_addc_u32 s29, s27, 0
	s_add_u32 s30, s28, 0x10000
	s_addc_u32 s31, s29, 0
	s_add_u32 s34, s30, 0x10000
	s_addc_u32 s35, s31, 0
	v_readfirstlane_b32 s36, v140
	v_mov_b32_e32 v254, v64
	s_mov_b32 m0, s36
	s_nop 0
	global_load_lds_dwordx4 v254, s[18:19]
	s_add_u32 m0, m0, 0x1000
	s_nop 0
	global_load_lds_dwordx4 v254, s[20:21]
	s_add_u32 m0, m0, 0x1000
	s_nop 0
	global_load_lds_dwordx4 v254, s[22:23]
	s_add_u32 m0, m0, 0x1000
	s_nop 0
	global_load_lds_dwordx4 v254, s[24:25]
	s_add_u32 m0, m0, 0x1000
	s_nop 0
	global_load_lds_dwordx4 v254, s[26:27]
	s_add_u32 m0, m0, 0x1000
	s_nop 0
	global_load_lds_dwordx4 v254, s[28:29]
	s_add_u32 m0, m0, 0x1000
	s_nop 0
	global_load_lds_dwordx4 v254, s[30:31]
	s_add_u32 m0, m0, 0x1000
	s_nop 0
	global_load_lds_dwordx4 v254, s[34:35]
	v_add_u32_e32 v254, 0x80, v254
	s_add_u32 m0, s36, 0x8000
	s_nop 0
	global_load_lds_dwordx4 v254, s[18:19]
	s_add_u32 m0, m0, 0x1000
	s_nop 0
	global_load_lds_dwordx4 v254, s[20:21]
	s_add_u32 m0, m0, 0x1000
	s_nop 0
	global_load_lds_dwordx4 v254, s[22:23]
	s_add_u32 m0, m0, 0x1000
	s_nop 0
	global_load_lds_dwordx4 v254, s[24:25]
	s_add_u32 m0, m0, 0x1000
	s_nop 0
	global_load_lds_dwordx4 v254, s[26:27]
	s_add_u32 m0, m0, 0x1000
	s_nop 0
	global_load_lds_dwordx4 v254, s[28:29]
	s_add_u32 m0, m0, 0x1000
	s_nop 0
	global_load_lds_dwordx4 v254, s[30:31]
	s_add_u32 m0, m0, 0x1000
	s_nop 0
	global_load_lds_dwordx4 v254, s[34:35]
	v_add_u32_e32 v254, 0x80, v254

.Lgk_nostag_p13:
	s_mul_i32 s38, s6, 0xb0000
	s_add_u32 s18, s14, s38
	s_addc_u32 s19, s15, 0
	s_add_u32 s18, s18, 0x879f000
	s_addc_u32 s19, s19, 0
	s_add_u32 s20, s18, 0x2c000
	s_addc_u32 s21, s19, 0
	s_add_u32 s22, s20, 0x2c000
	s_addc_u32 s23, s21, 0
	s_add_u32 s24, s22, 0x2c000
	s_addc_u32 s25, s23, 0
	s_mul_i32 s38, s64, 0xb0000
	s_add_u32 s26, s14, s38
	s_addc_u32 s27, s15, 0
	s_add_u32 s26, s26, 0x4b20000
	s_addc_u32 s27, s27, 0
	s_add_u32 s28, s26, 0x2c000
	s_addc_u32 s29, s27, 0
	s_add_u32 s30, s28, 0x2c000
	s_addc_u32 s31, s29, 0
	s_add_u32 s34, s30, 0x2c000
	s_addc_u32 s35, s31, 0
	v_readfirstlane_b32 s36, v141
	v_mov_b32_e32 v254, v64
	s_mov_b32 m0, s36
	s_nop 0
	global_load_lds_dwordx4 v254, s[18:19]
	s_add_u32 m0, m0, 0x1000
	s_nop 0
	global_load_lds_dwordx4 v254, s[20:21]
	s_add_u32 m0, m0, 0x1000
	s_nop 0
	global_load_lds_dwordx4 v254, s[22:23]
	s_add_u32 m0, m0, 0x1000
	s_nop 0
	global_load_lds_dwordx4 v254, s[24:25]
	s_add_u32 m0, m0, 0x1000
	s_nop 0
	global_load_lds_dwordx4 v254, s[26:27]
	s_add_u32 m0, m0, 0x1000
	s_nop 0
	global_load_lds_dwordx4 v254, s[28:29]
	s_add_u32 m0, m0, 0x1000
	s_nop 0
	global_load_lds_dwordx4 v254, s[30:31]
	s_add_u32 m0, m0, 0x1000
	s_nop 0
	global_load_lds_dwordx4 v254, s[34:35]
	v_add_u32_e32 v254, 0x80, v254
	s_add_u32 m0, s36, 0x8000
	s_nop 0
	global_load_lds_dwordx4 v254, s[18:19]
	s_add_u32 m0, m0, 0x1000
	s_nop 0
	global_load_lds_dwordx4 v254, s[20:21]
	s_add_u32 m0, m0, 0x1000
	s_nop 0
	global_load_lds_dwordx4 v254, s[22:23]
	s_add_u32 m0, m0, 0x1000
	s_nop 0
	global_load_lds_dwordx4 v254, s[24:25]
	s_add_u32 m0, m0, 0x1000
	s_nop 0
	global_load_lds_dwordx4 v254, s[26:27]
	s_add_u32 m0, m0, 0x1000
	s_nop 0
	global_load_lds_dwordx4 v254, s[28:29]
	s_add_u32 m0, m0, 0x1000
	s_nop 0
	global_load_lds_dwordx4 v254, s[30:31]
	s_add_u32 m0, m0, 0x1000
	s_nop 0
	global_load_lds_dwordx4 v254, s[34:35]
	v_add_u32_e32 v254, 0x80, v254

.Lgk_nostag_p16:
	s_lshl_b32 s38, s66, 11
	s_add_u32 s18, s14, s38
	s_addc_u32 s19, s15, 0
	s_add_u32 s18, s18, 0xb79f000
	s_addc_u32 s19, s19, 0
	s_add_u32 s20, s18, 0x10000
	s_addc_u32 s21, s19, 0
	s_add_u32 s22, s20, 0x10000
	s_addc_u32 s23, s21, 0
	s_add_u32 s24, s22, 0x10000
	s_addc_u32 s25, s23, 0
	s_lshl_b32 s38, s68, 11
	s_add_u32 s26, s14, s38
	s_addc_u32 s27, s15, 0
	s_add_u32 s26, s26, 0x10a0000
	s_addc_u32 s27, s27, 0
	s_add_u32 s28, s26, 0x10000
	s_addc_u32 s29, s27, 0
	s_add_u32 s30, s28, 0x10000
	s_addc_u32 s31, s29, 0
	s_add_u32 s34, s30, 0x10000
	s_addc_u32 s35, s31, 0
	v_readfirstlane_b32 s36, v140
	v_mov_b32_e32 v254, v64
	s_mov_b32 m0, s36
	s_nop 0
	global_load_lds_dwordx4 v254, s[18:19]
	s_add_u32 m0, m0, 0x1000
	s_nop 0
	global_load_lds_dwordx4 v254, s[20:21]
	s_add_u32 m0, m0, 0x1000
	s_nop 0
	global_load_lds_dwordx4 v254, s[22:23]
	s_add_u32 m0, m0, 0x1000
	s_nop 0
	global_load_lds_dwordx4 v254, s[24:25]
	s_add_u32 m0, m0, 0x1000
	s_nop 0
	global_load_lds_dwordx4 v254, s[26:27]
	s_add_u32 m0, m0, 0x1000
	s_nop 0
	global_load_lds_dwordx4 v254, s[28:29]
	s_add_u32 m0, m0, 0x1000
	s_nop 0
	global_load_lds_dwordx4 v254, s[30:31]
	s_add_u32 m0, m0, 0x1000
	s_nop 0
	global_load_lds_dwordx4 v254, s[34:35]
	v_add_u32_e32 v254, 0x80, v254
	s_add_u32 m0, s36, 0x8000
	s_nop 0
	global_load_lds_dwordx4 v254, s[18:19]
	s_add_u32 m0, m0, 0x1000
	s_nop 0
	global_load_lds_dwordx4 v254, s[20:21]
	s_add_u32 m0, m0, 0x1000
	s_nop 0
	global_load_lds_dwordx4 v254, s[22:23]
	s_add_u32 m0, m0, 0x1000
	s_nop 0
	global_load_lds_dwordx4 v254, s[24:25]
	s_add_u32 m0, m0, 0x1000
	s_nop 0
	global_load_lds_dwordx4 v254, s[26:27]
	s_add_u32 m0, m0, 0x1000
	s_nop 0
	global_load_lds_dwordx4 v254, s[28:29]
	s_add_u32 m0, m0, 0x1000
	s_nop 0
	global_load_lds_dwordx4 v254, s[30:31]
	s_add_u32 m0, m0, 0x1000
	s_nop 0
	global_load_lds_dwordx4 v254, s[34:35]
	v_add_u32_e32 v254, 0x80, v254

.Lgk_nostag_p18:
	s_mul_i32 s38, s6, 0xb0000
	s_add_u32 s18, s14, s38
	s_addc_u32 s19, s15, 0
	s_add_u32 s18, s18, 0x879f000
	s_addc_u32 s19, s19, 0
	s_add_u32 s20, s18, 0x2c000
	s_addc_u32 s21, s19, 0
	s_add_u32 s22, s20, 0x2c000
	s_addc_u32 s23, s21, 0
	s_add_u32 s24, s22, 0x2c000
	s_addc_u32 s25, s23, 0
	s_mul_i32 s38, s64, 0xb0000
	s_add_u32 s26, s14, s38
	s_addc_u32 s27, s15, 0
	s_add_u32 s26, s26, 0x50a0000
	s_addc_u32 s27, s27, 0
	s_add_u32 s28, s26, 0x2c000
	s_addc_u32 s29, s27, 0
	s_add_u32 s30, s28, 0x2c000
	s_addc_u32 s31, s29, 0
	s_add_u32 s34, s30, 0x2c000
	s_addc_u32 s35, s31, 0
	v_readfirstlane_b32 s36, v141
	v_mov_b32_e32 v254, v64
	s_mov_b32 m0, s36
	s_nop 0
	global_load_lds_dwordx4 v254, s[18:19]
	s_add_u32 m0, m0, 0x1000
	s_nop 0
	global_load_lds_dwordx4 v254, s[20:21]
	s_add_u32 m0, m0, 0x1000
	s_nop 0
	global_load_lds_dwordx4 v254, s[22:23]
	s_add_u32 m0, m0, 0x1000
	s_nop 0
	global_load_lds_dwordx4 v254, s[24:25]
	s_add_u32 m0, m0, 0x1000
	s_nop 0
	global_load_lds_dwordx4 v254, s[26:27]
	s_add_u32 m0, m0, 0x1000
	s_nop 0
	global_load_lds_dwordx4 v254, s[28:29]
	s_add_u32 m0, m0, 0x1000
	s_nop 0
	global_load_lds_dwordx4 v254, s[30:31]
	s_add_u32 m0, m0, 0x1000
	s_nop 0
	global_load_lds_dwordx4 v254, s[34:35]
	v_add_u32_e32 v254, 0x80, v254
	s_add_u32 m0, s36, 0x8000
	s_nop 0
	global_load_lds_dwordx4 v254, s[18:19]
	s_add_u32 m0, m0, 0x1000
	s_nop 0
	global_load_lds_dwordx4 v254, s[20:21]
	s_add_u32 m0, m0, 0x1000
	s_nop 0
	global_load_lds_dwordx4 v254, s[22:23]
	s_add_u32 m0, m0, 0x1000
	s_nop 0
	global_load_lds_dwordx4 v254, s[24:25]
	s_add_u32 m0, m0, 0x1000
	s_nop 0
	global_load_lds_dwordx4 v254, s[26:27]
	s_add_u32 m0, m0, 0x1000
	s_nop 0
	global_load_lds_dwordx4 v254, s[28:29]
	s_add_u32 m0, m0, 0x1000
	s_nop 0
	global_load_lds_dwordx4 v254, s[30:31]
	s_add_u32 m0, m0, 0x1000
	s_nop 0
	global_load_lds_dwordx4 v254, s[34:35]
	v_add_u32_e32 v254, 0x80, v254

.Lgk_nostag_p24:
	s_lshl_b32 s38, s66, 11
	s_add_u32 s18, s14, s38
	s_addc_u32 s19, s15, 0
	s_add_u32 s18, s18, 0xdf9f000
	s_addc_u32 s19, s19, 0
	s_add_u32 s20, s18, 0x10000
	s_addc_u32 s21, s19, 0
	s_add_u32 s22, s20, 0x10000
	s_addc_u32 s23, s21, 0
	s_add_u32 s24, s22, 0x10000
	s_addc_u32 s25, s23, 0
	s_lshl_b32 s38, s68, 11
	s_add_u32 s26, s14, s38
	s_addc_u32 s27, s15, 0
	s_add_u32 s26, s26, 0x17a0000
	s_addc_u32 s27, s27, 0
	s_add_u32 s28, s26, 0x10000
	s_addc_u32 s29, s27, 0
	s_add_u32 s30, s28, 0x10000
	s_addc_u32 s31, s29, 0
	s_add_u32 s34, s30, 0x10000
	s_addc_u32 s35, s31, 0
	v_readfirstlane_b32 s36, v140
	v_mov_b32_e32 v254, v64
	s_mov_b32 m0, s36
	s_nop 0
	global_load_lds_dwordx4 v254, s[18:19]
	s_add_u32 m0, m0, 0x1000
	s_nop 0
	global_load_lds_dwordx4 v254, s[20:21]
	s_add_u32 m0, m0, 0x1000
	s_nop 0
	global_load_lds_dwordx4 v254, s[22:23]
	s_add_u32 m0, m0, 0x1000
	s_nop 0
	global_load_lds_dwordx4 v254, s[24:25]
	s_add_u32 m0, m0, 0x1000
	s_nop 0
	global_load_lds_dwordx4 v254, s[26:27]
	s_add_u32 m0, m0, 0x1000
	s_nop 0
	global_load_lds_dwordx4 v254, s[28:29]
	s_add_u32 m0, m0, 0x1000
	s_nop 0
	global_load_lds_dwordx4 v254, s[30:31]
	s_add_u32 m0, m0, 0x1000
	s_nop 0
	global_load_lds_dwordx4 v254, s[34:35]
	v_add_u32_e32 v254, 0x80, v254
	s_add_u32 m0, s36, 0x8000
	s_nop 0
	global_load_lds_dwordx4 v254, s[18:19]
	s_add_u32 m0, m0, 0x1000
	s_nop 0
	global_load_lds_dwordx4 v254, s[20:21]
	s_add_u32 m0, m0, 0x1000
	s_nop 0
	global_load_lds_dwordx4 v254, s[22:23]
	s_add_u32 m0, m0, 0x1000
	s_nop 0
	global_load_lds_dwordx4 v254, s[24:25]
	s_add_u32 m0, m0, 0x1000
	s_nop 0
	global_load_lds_dwordx4 v254, s[26:27]
	s_add_u32 m0, m0, 0x1000
	s_nop 0
	global_load_lds_dwordx4 v254, s[28:29]
	s_add_u32 m0, m0, 0x1000
	s_nop 0
	global_load_lds_dwordx4 v254, s[30:31]
	s_add_u32 m0, m0, 0x1000
	s_nop 0
	global_load_lds_dwordx4 v254, s[34:35]
	v_add_u32_e32 v254, 0x80, v254

.LBB0_1637:
	s_ashr_i32 s2, s10, 31
	s_lshr_b32 s2, s2, 26
	s_add_i32 s2, s10, s2
	s_ashr_i32 s11, s2, 6
	s_andn2_b32 s2, s2, 63
	s_sub_i32 s2, s10, s2
	s_ashr_i32 s16, s2, 31
	s_lshr_b32 s16, s16, 29
	s_add_i32 s16, s2, s16
	s_and_b32 s52, s16, -8
	s_lshl_b32 s11, s11, 3
	s_sub_i32 s2, s2, s52
	s_add_i32 s2, s2, s11
	s_lshl_b32 s16, s16, 4
	s_lshl_b32 s11, s2, 7
	s_and_b32 s16, s16, 0xffffff80
	s_cmp_eq_u32 s39, 1
	s_cbranch_scc1 .Lgk_pfhead_p26
	s_bitcmp0_b32 s2, 8
	s_cbranch_scc1 .Lgk_nostag_p26
	s_sleep 127
	s_sleep 127
.Lgk_nostag_p26:
	s_mul_i32 s38, s2, 0xb0000
	s_add_u32 s18, s14, s38
	s_addc_u32 s19, s15, 0
	s_add_u32 s18, s18, 0x879f000
	s_addc_u32 s19, s19, 0
	s_add_u32 s20, s18, 0x2c000
	s_addc_u32 s21, s19, 0
	s_add_u32 s22, s20, 0x2c000
	s_addc_u32 s23, s21, 0
	s_add_u32 s24, s22, 0x2c000
	s_addc_u32 s25, s23, 0
	s_mul_i32 s38, s16, 0x1600
	s_add_u32 s26, s14, s38
	s_addc_u32 s27, s15, 0
	s_add_u32 s26, s26, 0x5620000
	s_addc_u32 s27, s27, 0
	s_add_u32 s28, s26, 0x2c000
	s_addc_u32 s29, s27, 0
	s_add_u32 s30, s28, 0x2c000
	s_addc_u32 s31, s29, 0
	s_add_u32 s34, s30, 0x2c000
	s_addc_u32 s35, s31, 0
	v_readfirstlane_b32 s36, v77
	v_mov_b32_e32 v254, v64
	s_mov_b32 m0, s36
	s_nop 0
	global_load_lds_dwordx4 v254, s[18:19]
	s_add_u32 m0, m0, 0x1000
	s_nop 0
	global_load_lds_dwordx4 v254, s[20:21]
	s_add_u32 m0, m0, 0x1000
	s_nop 0
	global_load_lds_dwordx4 v254, s[22:23]
	s_add_u32 m0, m0, 0x1000
	s_nop 0
	global_load_lds_dwordx4 v254, s[24:25]
	s_add_u32 m0, m0, 0x1000
	s_nop 0
	global_load_lds_dwordx4 v254, s[26:27]
	s_add_u32 m0, m0, 0x1000
	s_nop 0
	global_load_lds_dwordx4 v254, s[28:29]
	s_add_u32 m0, m0, 0x1000
	s_nop 0
	global_load_lds_dwordx4 v254, s[30:31]
	s_add_u32 m0, m0, 0x1000
	s_nop 0
	global_load_lds_dwordx4 v254, s[34:35]
	v_add_u32_e32 v254, 0x80, v254
	s_add_u32 m0, s36, 0x8000
	s_nop 0
	global_load_lds_dwordx4 v254, s[18:19]
	s_add_u32 m0, m0, 0x1000
	s_nop 0
	global_load_lds_dwordx4 v254, s[20:21]
	s_add_u32 m0, m0, 0x1000
	s_nop 0
	global_load_lds_dwordx4 v254, s[22:23]
	s_add_u32 m0, m0, 0x1000
	s_nop 0
	global_load_lds_dwordx4 v254, s[24:25]
	s_add_u32 m0, m0, 0x1000
	s_nop 0
	global_load_lds_dwordx4 v254, s[26:27]
	s_add_u32 m0, m0, 0x1000
	s_nop 0
	global_load_lds_dwordx4 v254, s[28:29]
	s_add_u32 m0, m0, 0x1000
	s_nop 0
	global_load_lds_dwordx4 v254, s[30:31]
	s_add_u32 m0, m0, 0x1000
	s_nop 0
	global_load_lds_dwordx4 v254, s[34:35]
	v_add_u32_e32 v254, 0x80, v254
